# P5 residual epilogue rewritten like P8: W_out^T rows stored permuted in P0 so each lane owns 8 contiguous columns; 16-byte f32 residual loads double-buffered, 16-byte bf16 stores
# speedup vs baseline: 1.0163x; 1.0086x over previous
.LBB0_66:
	v_ashrrev_i32_e32 v0, 31, v123
	v_lshrrev_b32_e32 v0, 27, v0
	v_add_u32_e32 v1, v123, v0
	v_and_b32_e32 v0, 0x3ffffe0, v1
	v_lshlrev_b32_e32 v1, 1, v1
	v_and_b32_e32 v62, 0xffffffc0, v1
	v_sub_u32_e32 v0, v123, v0
	v_or_b32_e32 v96, v62, v66
	v_lshlrev_b32_e32 v0, 6, v0
	v_or_b32_e32 v4, 4, v96
	v_ashrrev_i32_e32 v1, 31, v0
	v_ashrrev_i32_e32 v97, 31, v96
	v_ashrrev_i32_e32 v5, 31, v4
	v_lshl_add_u64 v[98:99], v[0:1], 2, v[82:83]
	v_lshlrev_b64 v[2:3], 13, v[96:97]
	v_lshlrev_b64 v[4:5], 13, v[4:5]
	v_lshl_add_u64 v[2:3], v[98:99], 0, v[2:3]
	v_lshl_add_u64 v[6:7], v[98:99], 0, v[4:5]
	v_or_b32_e32 v10, 8, v96
	v_or_b32_e32 v12, 12, v96
	global_load_dwordx4 v[2:5], v[2:3], off nt
	s_nop 0
	global_load_dwordx4 v[6:9], v[6:7], off nt
	v_ashrrev_i32_e32 v11, 31, v10
	v_ashrrev_i32_e32 v13, 31, v12
	v_lshlrev_b64 v[10:11], 13, v[10:11]
	v_lshlrev_b64 v[12:13], 13, v[12:13]
	v_lshl_add_u64 v[10:11], v[98:99], 0, v[10:11]
	v_lshl_add_u64 v[14:15], v[98:99], 0, v[12:13]
	global_load_dwordx4 v[10:13], v[10:11], off nt
	s_nop 0
	global_load_dwordx4 v[14:17], v[14:15], off nt
	v_or_b32_e32 v18, 16, v96
	v_or_b32_e32 v20, 20, v96
	v_ashrrev_i32_e32 v19, 31, v18
	v_ashrrev_i32_e32 v21, 31, v20
	v_lshlrev_b64 v[18:19], 13, v[18:19]
	v_lshlrev_b64 v[20:21], 13, v[20:21]
	v_lshl_add_u64 v[18:19], v[98:99], 0, v[18:19]
	v_lshl_add_u64 v[22:23], v[98:99], 0, v[20:21]
	global_load_dwordx4 v[18:21], v[18:19], off nt
	s_nop 0
	global_load_dwordx4 v[22:25], v[22:23], off nt
	v_or_b32_e32 v26, 24, v96
	v_or_b32_e32 v28, 28, v96
	v_ashrrev_i32_e32 v27, 31, v26
	v_ashrrev_i32_e32 v29, 31, v28
	v_lshlrev_b64 v[26:27], 13, v[26:27]
	v_lshlrev_b64 v[28:29], 13, v[28:29]
	v_lshl_add_u64 v[26:27], v[98:99], 0, v[26:27]
	v_lshl_add_u64 v[30:31], v[98:99], 0, v[28:29]
	global_load_dwordx4 v[26:29], v[26:27], off nt
	s_nop 0
	global_load_dwordx4 v[30:33], v[30:31], off nt
	v_or_b32_e32 v34, 32, v96
	v_or_b32_e32 v36, 36, v96
	v_ashrrev_i32_e32 v35, 31, v34
	v_ashrrev_i32_e32 v37, 31, v36
	v_lshlrev_b64 v[34:35], 13, v[34:35]
	v_lshlrev_b64 v[36:37], 13, v[36:37]
	v_lshl_add_u64 v[34:35], v[98:99], 0, v[34:35]
	v_lshl_add_u64 v[38:39], v[98:99], 0, v[36:37]
	global_load_dwordx4 v[34:37], v[34:35], off nt
	s_nop 0
	global_load_dwordx4 v[38:41], v[38:39], off nt
	v_or_b32_e32 v42, 40, v96
	v_or_b32_e32 v44, 44, v96
	v_ashrrev_i32_e32 v43, 31, v42
	v_ashrrev_i32_e32 v45, 31, v44
	v_lshlrev_b64 v[42:43], 13, v[42:43]
	v_lshlrev_b64 v[44:45], 13, v[44:45]
	v_lshl_add_u64 v[42:43], v[98:99], 0, v[42:43]
	v_lshl_add_u64 v[46:47], v[98:99], 0, v[44:45]
	v_or_b32_e32 v50, 48, v96
	global_load_dwordx4 v[42:45], v[42:43], off nt
	s_nop 0
	global_load_dwordx4 v[46:49], v[46:47], off nt
	v_ashrrev_i32_e32 v51, 31, v50
	v_lshlrev_b64 v[50:51], 13, v[50:51]
	v_or_b32_e32 v54, 52, v96
	v_lshl_add_u64 v[50:51], v[98:99], 0, v[50:51]
	v_ashrrev_i32_e32 v55, 31, v54
	global_load_dwordx4 v[50:53], v[50:51], off nt
	v_lshlrev_b64 v[54:55], 13, v[54:55]
	v_or_b32_e32 v58, 56, v96
	v_lshl_add_u64 v[54:55], v[98:99], 0, v[54:55]
	v_ashrrev_i32_e32 v59, 31, v58
	global_load_dwordx4 v[54:57], v[54:55], off nt
	v_lshlrev_b64 v[58:59], 13, v[58:59]
	v_or_b32_e32 v96, 60, v96
	v_lshl_add_u64 v[58:59], v[98:99], 0, v[58:59]
	v_ashrrev_i32_e32 v97, 31, v96
	global_load_dwordx4 v[58:61], v[58:59], off nt
	v_lshlrev_b64 v[96:97], 13, v[96:97]
	v_lshl_add_u64 v[96:97], v[98:99], 0, v[96:97]
	global_load_dwordx4 v[96:99], v[96:97], off nt
	v_add_u32_e32 v1, 0x410, v95
	v_ashrrev_i32_e32 v63, 31, v62
	s_waitcnt vmcnt(15)
	ds_write2_b32 v95, v2, v3 offset1:1
	ds_write2_b32 v95, v4, v5 offset0:2 offset1:3
	s_waitcnt vmcnt(14)
	ds_write2_b32 v1, v6, v7 offset1:1
	v_add_u32_e32 v1, 0x418, v95
	ds_write2_b32 v1, v8, v9 offset1:1
	v_add_u32_e32 v1, 0x820, v95
	v_lshl_add_u64 v[8:9], v[62:63], 1, v[68:69]
	s_waitcnt vmcnt(13)
	ds_write2_b32 v1, v10, v11 offset1:1
	v_add_u32_e32 v1, 0x828, v95
	ds_write2_b32 v1, v12, v13 offset1:1
	v_add_u32_e32 v1, 0xc30, v95
	s_waitcnt vmcnt(12)
	ds_write2_b32 v1, v14, v15 offset1:1
	v_add_u32_e32 v1, 0xc38, v95
	ds_write2_b32 v1, v16, v17 offset1:1
	v_add_u32_e32 v1, 0x1040, v95
	s_waitcnt vmcnt(11)
	ds_write2_b32 v1, v18, v19 offset1:1
	v_add_u32_e32 v1, 0x1048, v95
	ds_write2_b32 v1, v20, v21 offset1:1
	v_add_u32_e32 v1, 0x1450, v95
	s_waitcnt vmcnt(10)
	ds_write2_b32 v1, v22, v23 offset1:1
	v_add_u32_e32 v1, 0x1458, v95
	ds_write2_b32 v1, v24, v25 offset1:1
	v_add_u32_e32 v1, 0x1860, v95
	s_waitcnt vmcnt(9)
	ds_write2_b32 v1, v26, v27 offset1:1
	v_add_u32_e32 v1, 0x1868, v95
	ds_write2_b32 v1, v28, v29 offset1:1
	v_add_u32_e32 v1, 0x1c70, v95
	s_waitcnt vmcnt(8)
	ds_write2_b32 v1, v30, v31 offset1:1
	v_add_u32_e32 v1, 0x1c78, v95
	ds_write2_b32 v1, v32, v33 offset1:1
	v_add_u32_e32 v1, 0x2080, v95
	s_waitcnt vmcnt(7)
	ds_write2_b32 v1, v34, v35 offset1:1
	v_add_u32_e32 v1, 0x2088, v95
	ds_write2_b32 v1, v36, v37 offset1:1
	v_add_u32_e32 v1, 0x2490, v95
	s_waitcnt vmcnt(6)
	ds_write2_b32 v1, v38, v39 offset1:1
	v_add_u32_e32 v1, 0x2498, v95
	ds_write2_b32 v1, v40, v41 offset1:1
	v_add_u32_e32 v1, 0x28a0, v95
	s_waitcnt vmcnt(5)
	ds_write2_b32 v1, v42, v43 offset1:1
	v_add_u32_e32 v1, 0x28a8, v95
	ds_write2_b32 v1, v44, v45 offset1:1
	v_add_u32_e32 v1, 0x2cb0, v95
	s_waitcnt vmcnt(4)
	ds_write2_b32 v1, v46, v47 offset1:1
	v_add_u32_e32 v1, 0x2cb8, v95
	ds_write2_b32 v1, v48, v49 offset1:1
	v_add_u32_e32 v1, 0x30c0, v95
	s_waitcnt vmcnt(3)
	ds_write2_b32 v1, v50, v51 offset1:1
	v_add_u32_e32 v1, 0x30c8, v95
	ds_write2_b32 v1, v52, v53 offset1:1
	v_add_u32_e32 v1, 0x34d0, v95
	s_waitcnt vmcnt(2)
	ds_write2_b32 v1, v54, v55 offset1:1
	v_add_u32_e32 v1, 0x34d8, v95
	ds_write2_b32 v1, v56, v57 offset1:1
	v_add_u32_e32 v1, 0x38e0, v95
	s_waitcnt vmcnt(1)
	ds_write2_b32 v1, v58, v59 offset1:1
	v_add_u32_e32 v1, 0x38e8, v95
	ds_write2_b32 v1, v60, v61 offset1:1
	v_add_u32_e32 v1, 0x3cf0, v95
	s_waitcnt vmcnt(0)
	ds_write2_b32 v1, v96, v97 offset1:1
	v_add_u32_e32 v1, 0x3cf8, v95
	ds_write2_b32 v1, v98, v99 offset1:1
	s_waitcnt lgkmcnt(0)
	ds_read2_b32 v[2:3], v114 offset1:65
	s_waitcnt lgkmcnt(0)
	v_cvt_pk_bf16_f32 v2, v2, v3
	ds_read2_b32 v[4:5], v114 offset0:130 offset1:195
	v_add_u32_e32 v1, 0x400, v114
	s_waitcnt lgkmcnt(0)
	v_cvt_pk_bf16_f32 v3, v4, v5
	ds_read2_b32 v[4:5], v1 offset0:4 offset1:69
	s_waitcnt lgkmcnt(0)
	v_cvt_pk_bf16_f32 v4, v4, v5
	ds_read2_b32 v[6:7], v1 offset0:134 offset1:199
	s_waitcnt lgkmcnt(0)
	v_cvt_pk_bf16_f32 v5, v6, v7
	v_or_b32_e32 v6, 0, v254
	v_or_b32_e32 v6, v0, v6
	v_ashrrev_i32_e32 v7, 31, v6
	v_lshlrev_b64 v[6:7], 12, v[6:7]
	v_lshl_add_u64 v[6:7], v[8:9], 0, v[6:7]
	ds_read2_b32 v[10:11], v114 offset0:8 offset1:73
	global_store_dwordx4 v[6:7], v[2:5], off
	s_waitcnt lgkmcnt(0)
	s_nop 0
	v_cvt_pk_bf16_f32 v2, v10, v11
	ds_read2_b32 v[4:5], v114 offset0:138 offset1:203
	s_waitcnt lgkmcnt(0)
	v_cvt_pk_bf16_f32 v3, v4, v5
	ds_read2_b32 v[4:5], v1 offset0:12 offset1:77
	s_waitcnt lgkmcnt(0)
	v_cvt_pk_bf16_f32 v4, v4, v5
	ds_read2_b32 v[6:7], v1 offset0:142 offset1:207
	s_waitcnt lgkmcnt(0)
	v_cvt_pk_bf16_f32 v5, v6, v7
	v_or_b32_e32 v6, 4, v254
	v_or_b32_e32 v6, v0, v6
	v_ashrrev_i32_e32 v7, 31, v6
	v_lshlrev_b64 v[6:7], 12, v[6:7]
	v_lshl_add_u64 v[6:7], v[8:9], 0, v[6:7]
	ds_read2_b32 v[10:11], v114 offset0:16 offset1:81
	global_store_dwordx4 v[6:7], v[2:5], off
	s_waitcnt lgkmcnt(0)
	s_nop 0
	v_cvt_pk_bf16_f32 v2, v10, v11
	ds_read2_b32 v[4:5], v114 offset0:146 offset1:211
	s_waitcnt lgkmcnt(0)
	v_cvt_pk_bf16_f32 v3, v4, v5
	ds_read2_b32 v[4:5], v1 offset0:20 offset1:85
	s_waitcnt lgkmcnt(0)
	v_cvt_pk_bf16_f32 v4, v4, v5
	ds_read2_b32 v[6:7], v1 offset0:150 offset1:215
	s_waitcnt lgkmcnt(0)
	v_cvt_pk_bf16_f32 v5, v6, v7
	v_or_b32_e32 v6, 8, v254
	v_or_b32_e32 v6, v0, v6
	v_ashrrev_i32_e32 v7, 31, v6
	v_lshlrev_b64 v[6:7], 12, v[6:7]
	v_lshl_add_u64 v[6:7], v[8:9], 0, v[6:7]
	ds_read2_b32 v[10:11], v114 offset0:24 offset1:89
	global_store_dwordx4 v[6:7], v[2:5], off
	s_waitcnt lgkmcnt(0)
	s_nop 0
	v_cvt_pk_bf16_f32 v2, v10, v11
	ds_read2_b32 v[4:5], v114 offset0:154 offset1:219
	s_waitcnt lgkmcnt(0)
	v_cvt_pk_bf16_f32 v3, v4, v5
	ds_read2_b32 v[4:5], v1 offset0:28 offset1:93
	s_waitcnt lgkmcnt(0)
	v_cvt_pk_bf16_f32 v4, v4, v5
	ds_read2_b32 v[6:7], v1 offset0:158 offset1:223
	s_waitcnt lgkmcnt(0)
	v_cvt_pk_bf16_f32 v5, v6, v7
	v_or_b32_e32 v6, 12, v254
	v_or_b32_e32 v6, v0, v6
	v_ashrrev_i32_e32 v7, 31, v6
	v_lshlrev_b64 v[6:7], 12, v[6:7]
	v_lshl_add_u64 v[6:7], v[8:9], 0, v[6:7]
	ds_read2_b32 v[10:11], v114 offset0:32 offset1:97
	global_store_dwordx4 v[6:7], v[2:5], off
	s_waitcnt lgkmcnt(0)
	s_nop 0
	v_cvt_pk_bf16_f32 v2, v10, v11
	ds_read2_b32 v[4:5], v114 offset0:162 offset1:227
	s_waitcnt lgkmcnt(0)
	v_cvt_pk_bf16_f32 v3, v4, v5
	ds_read2_b32 v[4:5], v1 offset0:36 offset1:101
	s_waitcnt lgkmcnt(0)
	v_cvt_pk_bf16_f32 v4, v4, v5
	ds_read2_b32 v[6:7], v1 offset0:166 offset1:231
	s_waitcnt lgkmcnt(0)
	v_cvt_pk_bf16_f32 v5, v6, v7
	v_or_b32_e32 v6, 32, v254
	v_or_b32_e32 v6, v0, v6
	v_ashrrev_i32_e32 v7, 31, v6
	v_lshlrev_b64 v[6:7], 12, v[6:7]
	v_lshl_add_u64 v[6:7], v[8:9], 0, v[6:7]
	ds_read2_b32 v[10:11], v114 offset0:40 offset1:105
	global_store_dwordx4 v[6:7], v[2:5], off
	s_waitcnt lgkmcnt(0)
	s_nop 0
	v_cvt_pk_bf16_f32 v2, v10, v11
	ds_read2_b32 v[4:5], v114 offset0:170 offset1:235
	s_waitcnt lgkmcnt(0)
	v_cvt_pk_bf16_f32 v3, v4, v5
	ds_read2_b32 v[4:5], v1 offset0:44 offset1:109
	s_waitcnt lgkmcnt(0)
	v_cvt_pk_bf16_f32 v4, v4, v5
	ds_read2_b32 v[6:7], v1 offset0:174 offset1:239
	s_waitcnt lgkmcnt(0)
	v_cvt_pk_bf16_f32 v5, v6, v7
	v_or_b32_e32 v6, 36, v254
	v_or_b32_e32 v6, v0, v6
	v_ashrrev_i32_e32 v7, 31, v6
	v_lshlrev_b64 v[6:7], 12, v[6:7]
	v_lshl_add_u64 v[6:7], v[8:9], 0, v[6:7]
	ds_read2_b32 v[10:11], v114 offset0:48 offset1:113
	global_store_dwordx4 v[6:7], v[2:5], off
	s_waitcnt lgkmcnt(0)
	s_nop 0
	v_cvt_pk_bf16_f32 v2, v10, v11
	ds_read2_b32 v[4:5], v114 offset0:178 offset1:243
	s_waitcnt lgkmcnt(0)
	v_cvt_pk_bf16_f32 v3, v4, v5
	ds_read2_b32 v[4:5], v1 offset0:52 offset1:117
	s_waitcnt lgkmcnt(0)
	v_cvt_pk_bf16_f32 v4, v4, v5
	ds_read2_b32 v[6:7], v1 offset0:182 offset1:247
	s_waitcnt lgkmcnt(0)
	v_cvt_pk_bf16_f32 v5, v6, v7
	v_or_b32_e32 v6, 40, v254
	v_or_b32_e32 v6, v0, v6
	v_ashrrev_i32_e32 v7, 31, v6
	v_lshlrev_b64 v[6:7], 12, v[6:7]
	v_lshl_add_u64 v[6:7], v[8:9], 0, v[6:7]
	ds_read2_b32 v[10:11], v114 offset0:56 offset1:121
	global_store_dwordx4 v[6:7], v[2:5], off
	v_or_b32_e32 v255, 44, v254
	v_or_b32_e32 v0, v0, v255
	s_waitcnt lgkmcnt(0)
	v_cvt_pk_bf16_f32 v2, v10, v11
	ds_read2_b32 v[4:5], v114 offset0:186 offset1:251
	s_waitcnt lgkmcnt(0)
	v_cvt_pk_bf16_f32 v3, v4, v5
	ds_read2_b32 v[4:5], v1 offset0:60 offset1:125
	s_waitcnt lgkmcnt(0)
	v_cvt_pk_bf16_f32 v4, v4, v5
	ds_read2_b32 v[6:7], v1 offset0:190 offset1:255
	v_ashrrev_i32_e32 v1, 31, v0
	v_lshlrev_b64 v[0:1], 12, v[0:1]
	v_lshl_add_u64 v[0:1], v[8:9], 0, v[0:1]
	s_waitcnt lgkmcnt(0)
	v_cvt_pk_bf16_f32 v5, v6, v7
	global_store_dwordx4 v[0:1], v[2:5], off
	s_waitcnt lgkmcnt(0)
	s_or_b64 exec, exec, s[0:1]
	s_and_b64 exec, exec, vcc
	s_cbranch_execz .LBB0_24

.LBB0_1082:
	v_lshl_add_u32 v164, s47, 8, v148
	v_and_b32_e32 v155, 12, v150
	v_add_u32_e32 v155, v150, v155
	v_lshl_or_b32 v144, s22, 8, v155
	v_ashrrev_i32_e32 v165, 31, v164
	v_ashrrev_i32_e32 v145, 31, v144
	v_lshlrev_b64 v[156:157], 11, v[164:165]
	v_lshl_add_u64 v[156:157], v[156:157], 0, v[144:145]
	v_lshl_add_u64 v[160:161], v[156:157], 2, s[48:49]
	v_lshl_add_u64 v[162:163], v[156:157], 1, s[8:9]
	global_load_dwordx4 v[168:171], v[160:161], off
	global_load_dwordx4 v[172:175], v[160:161], off offset:16
	global_load_dwordx4 v[176:179], v[160:161], off offset:512
	global_load_dwordx4 v[180:183], v[160:161], off offset:528
	v_mov_b64_e32 v[216:217], v[160:161]
	v_mov_b64_e32 v[218:219], v[162:163]
	v_xor_b32_e32 v194, 16, v154
	v_lshlrev_b32_e32 v194, 2, v194
	v_xor_b32_e32 v195, 32, v154
	v_lshlrev_b32_e32 v195, 2, v195
	s_mov_b32 s90, 0x10000
	s_mov_b32 s91, 0
	s_mov_b32 s92, 0x80000
	s_mov_b32 s93, 0
	s_mov_b32 s94, 0x20000
	s_mov_b32 s95, 0
	s_mov_b32 s96, 0x100000
	s_mov_b32 s97, 0
	v_lshl_add_u64 v[160:161], v[160:161], 0, s[94:95]
	global_load_dwordx4 v[200:203], v[160:161], off
	global_load_dwordx4 v[204:207], v[160:161], off offset:16
	global_load_dwordx4 v[208:211], v[160:161], off offset:512
	global_load_dwordx4 v[212:215], v[160:161], off offset:528
	s_waitcnt vmcnt(4)
	v_pk_add_f32 v[124:125], v[124:125], v[168:169]
	v_pk_add_f32 v[126:127], v[126:127], v[170:171]
	v_cvt_pk_bf16_f32 v184, v124, v125
	v_cvt_pk_bf16_f32 v185, v126, v127
	v_mul_f32_e32 v192, v124, v124
	v_fmac_f32_e32 v192, v125, v125
	v_fmac_f32_e32 v192, v126, v126
	v_fmac_f32_e32 v192, v127, v127
	v_pk_add_f32 v[120:121], v[120:121], v[172:173]
	v_pk_add_f32 v[122:123], v[122:123], v[174:175]
	v_cvt_pk_bf16_f32 v186, v120, v121
	v_cvt_pk_bf16_f32 v187, v122, v123
	v_fmac_f32_e32 v192, v120, v120
	v_fmac_f32_e32 v192, v121, v121
	v_fmac_f32_e32 v192, v122, v122
	v_fmac_f32_e32 v192, v123, v123
	global_store_dwordx4 v[162:163], v[184:187], off
	v_pk_add_f32 v[116:117], v[116:117], v[176:177]
	v_pk_add_f32 v[118:119], v[118:119], v[178:179]
	v_cvt_pk_bf16_f32 v188, v116, v117
	v_cvt_pk_bf16_f32 v189, v118, v119
	v_fmac_f32_e32 v192, v116, v116
	v_fmac_f32_e32 v192, v117, v117
	v_fmac_f32_e32 v192, v118, v118
	v_fmac_f32_e32 v192, v119, v119
	v_pk_add_f32 v[112:113], v[112:113], v[180:181]
	v_pk_add_f32 v[114:115], v[114:115], v[182:183]
	v_cvt_pk_bf16_f32 v190, v112, v113
	v_cvt_pk_bf16_f32 v191, v114, v115
	v_fmac_f32_e32 v192, v112, v112
	v_fmac_f32_e32 v192, v113, v113
	v_fmac_f32_e32 v192, v114, v114
	v_fmac_f32_e32 v192, v115, v115
	global_store_dwordx4 v[162:163], v[188:191], off offset:256
	ds_bpermute_b32 v193, v194, v192
	s_waitcnt lgkmcnt(0)
	v_add_f32_e32 v192, v192, v193
	ds_bpermute_b32 v193, v195, v192
	v_lshl_add_u64 v[196:197], v[164:165], 2, s[10:11]
	s_waitcnt lgkmcnt(0)
	v_add_f32_e32 v192, v192, v193
	s_and_saveexec_b64 s[22:23], s[0:1]
	global_atomic_add_f32 v[196:197], v192, off
	s_or_b64 exec, exec, s[22:23]
	v_lshl_add_u64 v[162:163], v[162:163], 0, s[90:91]
	v_add_u32_e32 v164, 16, v164
	v_lshl_add_u64 v[160:161], v[160:161], 0, s[94:95]
	global_load_dwordx4 v[168:171], v[160:161], off
	global_load_dwordx4 v[172:175], v[160:161], off offset:16
	global_load_dwordx4 v[176:179], v[160:161], off offset:512
	global_load_dwordx4 v[180:183], v[160:161], off offset:528
	s_waitcnt vmcnt(6)
	v_pk_add_f32 v[108:109], v[108:109], v[200:201]
	v_pk_add_f32 v[110:111], v[110:111], v[202:203]
	v_cvt_pk_bf16_f32 v184, v108, v109
	v_cvt_pk_bf16_f32 v185, v110, v111
	v_mul_f32_e32 v192, v108, v108
	v_fmac_f32_e32 v192, v109, v109
	v_fmac_f32_e32 v192, v110, v110
	v_fmac_f32_e32 v192, v111, v111
	v_pk_add_f32 v[104:105], v[104:105], v[204:205]
	v_pk_add_f32 v[106:107], v[106:107], v[206:207]
	v_cvt_pk_bf16_f32 v186, v104, v105
	v_cvt_pk_bf16_f32 v187, v106, v107
	v_fmac_f32_e32 v192, v104, v104
	v_fmac_f32_e32 v192, v105, v105
	v_fmac_f32_e32 v192, v106, v106
	v_fmac_f32_e32 v192, v107, v107
	global_store_dwordx4 v[162:163], v[184:187], off
	v_pk_add_f32 v[100:101], v[100:101], v[208:209]
	v_pk_add_f32 v[102:103], v[102:103], v[210:211]
	v_cvt_pk_bf16_f32 v188, v100, v101
	v_cvt_pk_bf16_f32 v189, v102, v103
	v_fmac_f32_e32 v192, v100, v100
	v_fmac_f32_e32 v192, v101, v101
	v_fmac_f32_e32 v192, v102, v102
	v_fmac_f32_e32 v192, v103, v103
	v_pk_add_f32 v[96:97], v[96:97], v[212:213]
	v_pk_add_f32 v[98:99], v[98:99], v[214:215]
	v_cvt_pk_bf16_f32 v190, v96, v97
	v_cvt_pk_bf16_f32 v191, v98, v99
	v_fmac_f32_e32 v192, v96, v96
	v_fmac_f32_e32 v192, v97, v97
	v_fmac_f32_e32 v192, v98, v98
	v_fmac_f32_e32 v192, v99, v99
	global_store_dwordx4 v[162:163], v[188:191], off offset:256
	ds_bpermute_b32 v193, v194, v192
	s_waitcnt lgkmcnt(0)
	v_add_f32_e32 v192, v192, v193
	ds_bpermute_b32 v193, v195, v192
	v_lshl_add_u64 v[196:197], v[164:165], 2, s[10:11]
	s_waitcnt lgkmcnt(0)
	v_add_f32_e32 v192, v192, v193
	s_and_saveexec_b64 s[22:23], s[0:1]
	global_atomic_add_f32 v[196:197], v192, off
	s_or_b64 exec, exec, s[22:23]
	v_lshl_add_u64 v[162:163], v[162:163], 0, s[90:91]
	v_add_u32_e32 v164, 16, v164
	v_lshl_add_u64 v[160:161], v[160:161], 0, s[94:95]
	global_load_dwordx4 v[200:203], v[160:161], off
	global_load_dwordx4 v[204:207], v[160:161], off offset:16
	global_load_dwordx4 v[208:211], v[160:161], off offset:512
	global_load_dwordx4 v[212:215], v[160:161], off offset:528
	s_waitcnt vmcnt(6)
	v_pk_add_f32 v[92:93], v[92:93], v[168:169]
	v_pk_add_f32 v[94:95], v[94:95], v[170:171]
	v_cvt_pk_bf16_f32 v184, v92, v93
	v_cvt_pk_bf16_f32 v185, v94, v95
	v_mul_f32_e32 v192, v92, v92
	v_fmac_f32_e32 v192, v93, v93
	v_fmac_f32_e32 v192, v94, v94
	v_fmac_f32_e32 v192, v95, v95
	v_pk_add_f32 v[88:89], v[88:89], v[172:173]
	v_pk_add_f32 v[90:91], v[90:91], v[174:175]
	v_cvt_pk_bf16_f32 v186, v88, v89
	v_cvt_pk_bf16_f32 v187, v90, v91
	v_fmac_f32_e32 v192, v88, v88
	v_fmac_f32_e32 v192, v89, v89
	v_fmac_f32_e32 v192, v90, v90
	v_fmac_f32_e32 v192, v91, v91
	global_store_dwordx4 v[162:163], v[184:187], off
	v_pk_add_f32 v[84:85], v[84:85], v[176:177]
	v_pk_add_f32 v[86:87], v[86:87], v[178:179]
	v_cvt_pk_bf16_f32 v188, v84, v85
	v_cvt_pk_bf16_f32 v189, v86, v87
	v_fmac_f32_e32 v192, v84, v84
	v_fmac_f32_e32 v192, v85, v85
	v_fmac_f32_e32 v192, v86, v86
	v_fmac_f32_e32 v192, v87, v87
	v_pk_add_f32 v[80:81], v[80:81], v[180:181]
	v_pk_add_f32 v[82:83], v[82:83], v[182:183]
	v_cvt_pk_bf16_f32 v190, v80, v81
	v_cvt_pk_bf16_f32 v191, v82, v83
	v_fmac_f32_e32 v192, v80, v80
	v_fmac_f32_e32 v192, v81, v81
	v_fmac_f32_e32 v192, v82, v82
	v_fmac_f32_e32 v192, v83, v83
	global_store_dwordx4 v[162:163], v[188:191], off offset:256
	ds_bpermute_b32 v193, v194, v192
	s_waitcnt lgkmcnt(0)
	v_add_f32_e32 v192, v192, v193
	ds_bpermute_b32 v193, v195, v192
	v_lshl_add_u64 v[196:197], v[164:165], 2, s[10:11]
	s_waitcnt lgkmcnt(0)
	v_add_f32_e32 v192, v192, v193
	s_and_saveexec_b64 s[22:23], s[0:1]
	global_atomic_add_f32 v[196:197], v192, off
	s_or_b64 exec, exec, s[22:23]
	v_lshl_add_u64 v[162:163], v[162:163], 0, s[90:91]
	v_add_u32_e32 v164, 16, v164
	v_lshl_add_u64 v[160:161], v[216:217], 0, s[96:97]
	global_load_dwordx4 v[168:171], v[160:161], off
	global_load_dwordx4 v[172:175], v[160:161], off offset:16
	global_load_dwordx4 v[176:179], v[160:161], off offset:512
	global_load_dwordx4 v[180:183], v[160:161], off offset:528
	s_waitcnt vmcnt(6)
	v_pk_add_f32 v[76:77], v[76:77], v[200:201]
	v_pk_add_f32 v[78:79], v[78:79], v[202:203]
	v_cvt_pk_bf16_f32 v184, v76, v77
	v_cvt_pk_bf16_f32 v185, v78, v79
	v_mul_f32_e32 v192, v76, v76
	v_fmac_f32_e32 v192, v77, v77
	v_fmac_f32_e32 v192, v78, v78
	v_fmac_f32_e32 v192, v79, v79
	v_pk_add_f32 v[72:73], v[72:73], v[204:205]
	v_pk_add_f32 v[74:75], v[74:75], v[206:207]
	v_cvt_pk_bf16_f32 v186, v72, v73
	v_cvt_pk_bf16_f32 v187, v74, v75
	v_fmac_f32_e32 v192, v72, v72
	v_fmac_f32_e32 v192, v73, v73
	v_fmac_f32_e32 v192, v74, v74
	v_fmac_f32_e32 v192, v75, v75
	global_store_dwordx4 v[162:163], v[184:187], off
	v_pk_add_f32 v[68:69], v[68:69], v[208:209]
	v_pk_add_f32 v[70:71], v[70:71], v[210:211]
	v_cvt_pk_bf16_f32 v188, v68, v69
	v_cvt_pk_bf16_f32 v189, v70, v71
	v_fmac_f32_e32 v192, v68, v68
	v_fmac_f32_e32 v192, v69, v69
	v_fmac_f32_e32 v192, v70, v70
	v_fmac_f32_e32 v192, v71, v71
	v_pk_add_f32 v[64:65], v[64:65], v[212:213]
	v_pk_add_f32 v[66:67], v[66:67], v[214:215]
	v_cvt_pk_bf16_f32 v190, v64, v65
	v_cvt_pk_bf16_f32 v191, v66, v67
	v_fmac_f32_e32 v192, v64, v64
	v_fmac_f32_e32 v192, v65, v65
	v_fmac_f32_e32 v192, v66, v66
	v_fmac_f32_e32 v192, v67, v67
	global_store_dwordx4 v[162:163], v[188:191], off offset:256
	ds_bpermute_b32 v193, v194, v192
	s_waitcnt lgkmcnt(0)
	v_add_f32_e32 v192, v192, v193
	ds_bpermute_b32 v193, v195, v192
	v_lshl_add_u64 v[196:197], v[164:165], 2, s[10:11]
	s_waitcnt lgkmcnt(0)
	v_add_f32_e32 v192, v192, v193
	s_and_saveexec_b64 s[22:23], s[0:1]
	global_atomic_add_f32 v[196:197], v192, off
	s_or_b64 exec, exec, s[22:23]
	v_lshl_add_u64 v[162:163], v[218:219], 0, s[92:93]
	v_add_u32_e32 v164, 0x50, v164
	v_lshl_add_u64 v[160:161], v[160:161], 0, s[94:95]
	global_load_dwordx4 v[200:203], v[160:161], off
	global_load_dwordx4 v[204:207], v[160:161], off offset:16
	global_load_dwordx4 v[208:211], v[160:161], off offset:512
	global_load_dwordx4 v[212:215], v[160:161], off offset:528
	s_waitcnt vmcnt(6)
	v_pk_add_f32 v[60:61], v[60:61], v[168:169]
	v_pk_add_f32 v[62:63], v[62:63], v[170:171]
	v_cvt_pk_bf16_f32 v184, v60, v61
	v_cvt_pk_bf16_f32 v185, v62, v63
	v_mul_f32_e32 v192, v60, v60
	v_fmac_f32_e32 v192, v61, v61
	v_fmac_f32_e32 v192, v62, v62
	v_fmac_f32_e32 v192, v63, v63
	v_pk_add_f32 v[56:57], v[56:57], v[172:173]
	v_pk_add_f32 v[58:59], v[58:59], v[174:175]
	v_cvt_pk_bf16_f32 v186, v56, v57
	v_cvt_pk_bf16_f32 v187, v58, v59
	v_fmac_f32_e32 v192, v56, v56
	v_fmac_f32_e32 v192, v57, v57
	v_fmac_f32_e32 v192, v58, v58
	v_fmac_f32_e32 v192, v59, v59
	global_store_dwordx4 v[162:163], v[184:187], off
	v_pk_add_f32 v[52:53], v[52:53], v[176:177]
	v_pk_add_f32 v[54:55], v[54:55], v[178:179]
	v_cvt_pk_bf16_f32 v188, v52, v53
	v_cvt_pk_bf16_f32 v189, v54, v55
	v_fmac_f32_e32 v192, v52, v52
	v_fmac_f32_e32 v192, v53, v53
	v_fmac_f32_e32 v192, v54, v54
	v_fmac_f32_e32 v192, v55, v55
	v_pk_add_f32 v[48:49], v[48:49], v[180:181]
	v_pk_add_f32 v[50:51], v[50:51], v[182:183]
	v_cvt_pk_bf16_f32 v190, v48, v49
	v_cvt_pk_bf16_f32 v191, v50, v51
	v_fmac_f32_e32 v192, v48, v48
	v_fmac_f32_e32 v192, v49, v49
	v_fmac_f32_e32 v192, v50, v50
	v_fmac_f32_e32 v192, v51, v51
	global_store_dwordx4 v[162:163], v[188:191], off offset:256
	ds_bpermute_b32 v193, v194, v192
	s_waitcnt lgkmcnt(0)
	v_add_f32_e32 v192, v192, v193
	ds_bpermute_b32 v193, v195, v192
	v_lshl_add_u64 v[196:197], v[164:165], 2, s[10:11]
	s_waitcnt lgkmcnt(0)
	v_add_f32_e32 v192, v192, v193
	s_and_saveexec_b64 s[22:23], s[0:1]
	global_atomic_add_f32 v[196:197], v192, off
	s_or_b64 exec, exec, s[22:23]
	v_lshl_add_u64 v[162:163], v[162:163], 0, s[90:91]
	v_add_u32_e32 v164, 16, v164
	v_lshl_add_u64 v[160:161], v[160:161], 0, s[94:95]
	global_load_dwordx4 v[168:171], v[160:161], off
	global_load_dwordx4 v[172:175], v[160:161], off offset:16
	global_load_dwordx4 v[176:179], v[160:161], off offset:512
	global_load_dwordx4 v[180:183], v[160:161], off offset:528
	s_waitcnt vmcnt(6)
	v_pk_add_f32 v[44:45], v[44:45], v[200:201]
	v_pk_add_f32 v[46:47], v[46:47], v[202:203]
	v_cvt_pk_bf16_f32 v184, v44, v45
	v_cvt_pk_bf16_f32 v185, v46, v47
	v_mul_f32_e32 v192, v44, v44
	v_fmac_f32_e32 v192, v45, v45
	v_fmac_f32_e32 v192, v46, v46
	v_fmac_f32_e32 v192, v47, v47
	v_pk_add_f32 v[40:41], v[40:41], v[204:205]
	v_pk_add_f32 v[42:43], v[42:43], v[206:207]
	v_cvt_pk_bf16_f32 v186, v40, v41
	v_cvt_pk_bf16_f32 v187, v42, v43
	v_fmac_f32_e32 v192, v40, v40
	v_fmac_f32_e32 v192, v41, v41
	v_fmac_f32_e32 v192, v42, v42
	v_fmac_f32_e32 v192, v43, v43
	global_store_dwordx4 v[162:163], v[184:187], off
	v_pk_add_f32 v[36:37], v[36:37], v[208:209]
	v_pk_add_f32 v[38:39], v[38:39], v[210:211]
	v_cvt_pk_bf16_f32 v188, v36, v37
	v_cvt_pk_bf16_f32 v189, v38, v39
	v_fmac_f32_e32 v192, v36, v36
	v_fmac_f32_e32 v192, v37, v37
	v_fmac_f32_e32 v192, v38, v38
	v_fmac_f32_e32 v192, v39, v39
	v_pk_add_f32 v[32:33], v[32:33], v[212:213]
	v_pk_add_f32 v[34:35], v[34:35], v[214:215]
	v_cvt_pk_bf16_f32 v190, v32, v33
	v_cvt_pk_bf16_f32 v191, v34, v35
	v_fmac_f32_e32 v192, v32, v32
	v_fmac_f32_e32 v192, v33, v33
	v_fmac_f32_e32 v192, v34, v34
	v_fmac_f32_e32 v192, v35, v35
	global_store_dwordx4 v[162:163], v[188:191], off offset:256
	ds_bpermute_b32 v193, v194, v192
	s_waitcnt lgkmcnt(0)
	v_add_f32_e32 v192, v192, v193
	ds_bpermute_b32 v193, v195, v192
	v_lshl_add_u64 v[196:197], v[164:165], 2, s[10:11]
	s_waitcnt lgkmcnt(0)
	v_add_f32_e32 v192, v192, v193
	s_and_saveexec_b64 s[22:23], s[0:1]
	global_atomic_add_f32 v[196:197], v192, off
	s_or_b64 exec, exec, s[22:23]
	v_lshl_add_u64 v[162:163], v[162:163], 0, s[90:91]
	v_add_u32_e32 v164, 16, v164
	v_lshl_add_u64 v[160:161], v[160:161], 0, s[94:95]
	global_load_dwordx4 v[200:203], v[160:161], off
	global_load_dwordx4 v[204:207], v[160:161], off offset:16
	global_load_dwordx4 v[208:211], v[160:161], off offset:512
	global_load_dwordx4 v[212:215], v[160:161], off offset:528
	s_waitcnt vmcnt(6)
	v_pk_add_f32 v[28:29], v[28:29], v[168:169]
	v_pk_add_f32 v[30:31], v[30:31], v[170:171]
	v_cvt_pk_bf16_f32 v184, v28, v29
	v_cvt_pk_bf16_f32 v185, v30, v31
	v_mul_f32_e32 v192, v28, v28
	v_fmac_f32_e32 v192, v29, v29
	v_fmac_f32_e32 v192, v30, v30
	v_fmac_f32_e32 v192, v31, v31
	v_pk_add_f32 v[24:25], v[24:25], v[172:173]
	v_pk_add_f32 v[26:27], v[26:27], v[174:175]
	v_cvt_pk_bf16_f32 v186, v24, v25
	v_cvt_pk_bf16_f32 v187, v26, v27
	v_fmac_f32_e32 v192, v24, v24
	v_fmac_f32_e32 v192, v25, v25
	v_fmac_f32_e32 v192, v26, v26
	v_fmac_f32_e32 v192, v27, v27
	global_store_dwordx4 v[162:163], v[184:187], off
	v_pk_add_f32 v[20:21], v[20:21], v[176:177]
	v_pk_add_f32 v[22:23], v[22:23], v[178:179]
	v_cvt_pk_bf16_f32 v188, v20, v21
	v_cvt_pk_bf16_f32 v189, v22, v23
	v_fmac_f32_e32 v192, v20, v20
	v_fmac_f32_e32 v192, v21, v21
	v_fmac_f32_e32 v192, v22, v22
	v_fmac_f32_e32 v192, v23, v23
	v_pk_add_f32 v[16:17], v[16:17], v[180:181]
	v_pk_add_f32 v[18:19], v[18:19], v[182:183]
	v_cvt_pk_bf16_f32 v190, v16, v17
	v_cvt_pk_bf16_f32 v191, v18, v19
	v_fmac_f32_e32 v192, v16, v16
	v_fmac_f32_e32 v192, v17, v17
	v_fmac_f32_e32 v192, v18, v18
	v_fmac_f32_e32 v192, v19, v19
	global_store_dwordx4 v[162:163], v[188:191], off offset:256
	ds_bpermute_b32 v193, v194, v192
	s_waitcnt lgkmcnt(0)
	v_add_f32_e32 v192, v192, v193
	ds_bpermute_b32 v193, v195, v192
	v_lshl_add_u64 v[196:197], v[164:165], 2, s[10:11]
	s_waitcnt lgkmcnt(0)
	v_add_f32_e32 v192, v192, v193
	s_and_saveexec_b64 s[22:23], s[0:1]
	global_atomic_add_f32 v[196:197], v192, off
	s_or_b64 exec, exec, s[22:23]
	v_lshl_add_u64 v[162:163], v[162:163], 0, s[90:91]
	v_add_u32_e32 v164, 16, v164
	s_waitcnt vmcnt(2)
	v_pk_add_f32 v[12:13], v[12:13], v[200:201]
	v_pk_add_f32 v[14:15], v[14:15], v[202:203]
	v_cvt_pk_bf16_f32 v184, v12, v13
	v_cvt_pk_bf16_f32 v185, v14, v15
	v_mul_f32_e32 v192, v12, v12
	v_fmac_f32_e32 v192, v13, v13
	v_fmac_f32_e32 v192, v14, v14
	v_fmac_f32_e32 v192, v15, v15
	v_pk_add_f32 v[8:9], v[8:9], v[204:205]
	v_pk_add_f32 v[10:11], v[10:11], v[206:207]
	v_cvt_pk_bf16_f32 v186, v8, v9
	v_cvt_pk_bf16_f32 v187, v10, v11
	v_fmac_f32_e32 v192, v8, v8
	v_fmac_f32_e32 v192, v9, v9
	v_fmac_f32_e32 v192, v10, v10
	v_fmac_f32_e32 v192, v11, v11
	global_store_dwordx4 v[162:163], v[184:187], off
	v_pk_add_f32 v[4:5], v[4:5], v[208:209]
	v_pk_add_f32 v[6:7], v[6:7], v[210:211]
	v_cvt_pk_bf16_f32 v188, v4, v5
	v_cvt_pk_bf16_f32 v189, v6, v7
	v_fmac_f32_e32 v192, v4, v4
	v_fmac_f32_e32 v192, v5, v5
	v_fmac_f32_e32 v192, v6, v6
	v_fmac_f32_e32 v192, v7, v7
	v_pk_add_f32 v[0:1], v[0:1], v[212:213]
	v_pk_add_f32 v[2:3], v[2:3], v[214:215]
	v_cvt_pk_bf16_f32 v190, v0, v1
	v_cvt_pk_bf16_f32 v191, v2, v3
	v_fmac_f32_e32 v192, v0, v0
	v_fmac_f32_e32 v192, v1, v1
	v_fmac_f32_e32 v192, v2, v2
	v_fmac_f32_e32 v192, v3, v3
	global_store_dwordx4 v[162:163], v[188:191], off offset:256
	ds_bpermute_b32 v193, v194, v192
	s_waitcnt lgkmcnt(0)
	v_add_f32_e32 v192, v192, v193
	ds_bpermute_b32 v193, v195, v192
	v_lshl_add_u64 v[196:197], v[164:165], 2, s[10:11]
	s_waitcnt lgkmcnt(0)
	v_add_f32_e32 v192, v192, v193
	s_and_saveexec_b64 s[22:23], s[0:1]
	global_atomic_add_f32 v[196:197], v192, off
	s_or_b64 exec, exec, s[22:23]
	s_andn2_b64 vcc, exec, s[2:3]
	s_mov_b64 s[2:3], -1
	s_cbranch_vccnz .LBB0_1069
	s_andn2_b64 vcc, exec, s[6:7]
	s_cbranch_vccnz .LBB0_1068
	s_barrier
	s_branch .LBB0_1068
